# phase-1 stage order swapped (SGU first) for every second workgroup within each XCD (bit 3 of the workgroup id) instead of by XCD parity
# baseline (speedup 1.0000x reference)
; __device__ __forceinline__ int lane_op() { unsigned z = 0u; asm volatile("" : "+v"(z)); return (int)__builtin_amdgcn_mbcnt_hi(~0u, __builtin_amdgcn_mbcnt_lo(~0u, z)); }
; #define PH_ON(bit) if constexpr ((PHMASK & (bit)) != 0)
; __global__ void __launch_bounds__(NTHREADS, 2) fwd_megakernel(Args a_unused) {
;     ...
;                 const int per = (1024 + G - 1) / G;
;                 PH_ON(512) {
;                     const int lane = lane_op();
;                     const float la = wave_sum(ap->in[I_LQ1][l * 64 + lane] * ap->in[I_LK1][l * 64 + lane]), lb = wave_sum(ap->in[I_LQ2][l * 64 + lane] * ap->in[I_LK2][l * 64 + lane]);
;                     const float lam_init = 0.8f - 0.6f * expf(-0.3f * (float)l);
;                     const float lam = __int_as_float(__builtin_amdgcn_readfirstlane(__float_as_int(expf(la) - expf(lb) + lam_init)));
;                     const float oscale = __int_as_float(__builtin_amdgcn_readfirstlane(__float_as_int(1.0f - lam_init)));
;                     const float* subg = ap->in[I_SUBG] + l * 128;
;                     if constexpr (PROBE_ATT2 != 0) { for (int i = 0; i < per; ++i) { const int u = vcu * per + i; if (u < 1024) attn_unit<false>(lds, (bf16_t*)(ws + WS_Q), (const bf16_t*)(ws + WS_K), (const bf16_t*)(ws + WS_VT), subg, lam, oscale, u, wave); } }
;                     for (int i = 0; i < per; ++i) { int u = vcu * per + i;
;                         if (G == 256) { const int bb = vcu >> 5, w = vcu & 31; u = ((bb * 8 + 2 * i + (w >> 4)) << 4) | (w & 15); }
;                         if (u < 1024) attn_unit<true>(lds, (bf16_t*)(ws + WS_Q), (const bf16_t*)(ws + WS_K), (const bf16_t*)(ws + WS_VT), subg, lam, oscale, u, wave); }
.Lph1_setup:
	v_mov_b32_e32 v0, v1
	s_load_dwordx8 s[40:47], s[0:1], 0x48
	v_mbcnt_lo_u32_b32 v0, -1, v0
	v_readlane_b32 s12, v254, 60
	v_mbcnt_hi_u32_b32 v0, -1, v0
	s_waitcnt lgkmcnt(0)
	s_mov_b32 s14, s12
	v_lshl_add_u32 v2, s14, 6, v0
	v_ashrrev_i32_e32 v3, 31, v2
	v_lshlrev_b64 v[2:3], 2, v[2:3]
	v_lshl_add_u64 v[4:5], s[40:41], 0, v[2:3]
	global_load_dword v0, v[4:5], off
	v_lshl_add_u64 v[4:5], s[42:43], 0, v[2:3]
	global_load_dword v6, v[4:5], off
	v_mov_b32_e32 v7, v195
	v_lshl_add_u64 v[4:5], s[44:45], 0, v[2:3]
	v_lshl_add_u64 v[2:3], s[46:47], 0, v[2:3]
	global_load_dword v4, v[4:5], off
	s_abs_i32 s7, s29
	global_load_dword v2, v[2:3], off
	v_cvt_f32_i32_e32 v5, s14
	v_cvt_f32_u32_e32 v8, s7
	s_mov_b32 s19, 0x3fb8aa3b
	s_add_i32 s12, s29, 0x3ff
	v_mul_f32_e32 v5, 0xbe99999a, v5
	v_rcp_iflag_f32_e32 v8, v8
	v_mul_f32_e32 v9, 0x3fb8aa3b, v5
	v_fma_f32 v10, v5, s19, -v9
	v_rndne_f32_e32 v11, v9
	v_fmac_f32_e32 v10, 0x32a5705f, v5
	v_sub_f32_e32 v9, v9, v11
	v_add_f32_e32 v9, v9, v10
	v_cvt_i32_f32_e32 v11, v11
	v_mul_f32_e32 v8, 0x4f7ffffe, v8
	v_exp_f32_e32 v9, v9
	v_cvt_u32_f32_e32 v8, v8
	s_mov_b32 s20, 0xc2ce8ed0
	v_readlane_b32 s13, v254, 61
	v_mov_b32_e32 v3, v195
	s_xor_b32 s14, s12, s29
	v_ldexp_f32 v9, v9, v11
	v_cmp_ngt_f32_e32 vcc, s20, v5
	s_mov_b32 s21, 0x42b17218
	s_abs_i32 s13, s12
	s_ashr_i32 s12, s14, 31
	v_lshlrev_b32_e32 v7, 2, v7
	v_readfirstlane_b32 s14, v8
	v_cndmask_b32_e32 v8, 0, v9, vcc
	v_cmp_nlt_f32_e32 vcc, s21, v5
	v_mov_b32_e32 v11, 0x7f800000
	v_lshlrev_b32_e32 v3, 2, v3
	v_xor_b32_e32 v10, 4, v7
	v_cndmask_b32_e32 v5, v11, v8, vcc
	v_xor_b32_e32 v16, 4, v3
	v_xor_b32_e32 v12, 8, v7
	v_xor_b32_e32 v17, 8, v3
	v_xor_b32_e32 v13, 16, v7
	v_xor_b32_e32 v18, 16, v3
	v_xor_b32_e32 v14, 32, v7
	v_xor_b32_e32 v19, 32, v3
	v_xor_b32_e32 v15, 64, v7
	v_xor_b32_e32 v20, 64, v3
	v_xor_b32_e32 v7, 0x80, v7
	v_xor_b32_e32 v3, 0x80, v3
	s_sub_i32 s15, 0, s7
	s_mul_i32 s15, s15, s14
	s_mul_hi_u32 s15, s14, s15
	s_add_i32 s14, s14, s15
	s_mul_hi_u32 s14, s13, s14
	s_mul_i32 s16, s14, s7
	s_sub_i32 s13, s13, s16
	s_add_i32 s18, s14, 1
	s_sub_i32 s16, s13, s7
	s_cmp_ge_u32 s13, s7
	s_cselect_b32 s14, s18, s14
	s_cselect_b32 s13, s16, s13
	s_add_i32 s16, s14, 1
	s_cmp_ge_u32 s13, s7
	s_cselect_b32 s7, s16, s14
	s_xor_b32 s7, s7, s12
	s_sub_i32 s7, s7, s12
	s_cmp_gt_i32 s7, 0
	s_cselect_b64 s[12:13], -1, 0
	v_writelane_b32 v254, s12, 62
	s_cmp_lt_i32 s7, 1
	s_waitcnt vmcnt(0)
	v_mul_f32_e32 v8, v0, v6
	ds_bpermute_b32 v8, v10, v8
	v_mov_b32_e32 v10, 0x3f4ccccd
	v_fmamk_f32 v5, v5, 0xbf19999a, v10
	v_writelane_b32 v254, s13, 63
	v_readfirstlane_b32 s15, v5
	s_waitcnt lgkmcnt(0)
	v_fmac_f32_e32 v8, v0, v6
	v_mul_f32_e32 v9, v4, v2
	ds_bpermute_b32 v9, v16, v9
	ds_bpermute_b32 v0, v12, v8
	v_readlane_b32 s12, v254, 59
	s_mul_i32 s39, s7, s12
	s_waitcnt lgkmcnt(1)
	v_fmac_f32_e32 v9, v4, v2
	ds_bpermute_b32 v2, v17, v9
	s_waitcnt lgkmcnt(1)
	v_add_f32_e32 v0, v8, v0
	ds_bpermute_b32 v4, v13, v0
	s_waitcnt lgkmcnt(1)
	v_add_f32_e32 v2, v9, v2
	ds_bpermute_b32 v6, v18, v2
	s_waitcnt lgkmcnt(1)
	v_add_f32_e32 v0, v0, v4
	ds_bpermute_b32 v4, v14, v0
	s_waitcnt lgkmcnt(1)
	v_add_f32_e32 v2, v2, v6
	ds_bpermute_b32 v6, v19, v2
	s_waitcnt lgkmcnt(1)
	v_add_f32_e32 v0, v0, v4
	ds_bpermute_b32 v4, v15, v0
	s_waitcnt lgkmcnt(1)
	v_add_f32_e32 v2, v2, v6
	ds_bpermute_b32 v6, v20, v2
	s_waitcnt lgkmcnt(1)
	v_add_f32_e32 v0, v0, v4
	ds_bpermute_b32 v4, v7, v0
	s_waitcnt lgkmcnt(1)
	v_add_f32_e32 v2, v2, v6
	ds_bpermute_b32 v3, v3, v2
	s_waitcnt lgkmcnt(1)
	v_add_f32_e32 v0, v0, v4
	v_cmp_ngt_f32_e32 vcc, s20, v0
	s_waitcnt lgkmcnt(0)
	v_add_f32_e32 v2, v2, v3
	v_mul_f32_e32 v3, 0x3fb8aa3b, v0
	v_mul_f32_e32 v4, 0x3fb8aa3b, v2
	v_fma_f32 v6, v0, s19, -v3
	v_rndne_f32_e32 v7, v3
	v_fma_f32 v8, v2, s19, -v4
	v_rndne_f32_e32 v9, v4
	v_fmac_f32_e32 v6, 0x32a5705f, v0
	v_sub_f32_e32 v3, v3, v7
	v_fmac_f32_e32 v8, 0x32a5705f, v2
	v_sub_f32_e32 v4, v4, v9
	v_add_f32_e32 v3, v3, v6
	v_cvt_i32_f32_e32 v7, v7
	v_add_f32_e32 v4, v4, v8
	v_exp_f32_e32 v3, v3
	v_cvt_i32_f32_e32 v9, v9
	v_exp_f32_e32 v4, v4
	v_ldexp_f32 v3, v3, v7
	v_cndmask_b32_e32 v3, 0, v3, vcc
	v_ldexp_f32 v4, v4, v9
	v_cmp_ngt_f32_e32 vcc, s20, v2
	s_nop 1
	v_cndmask_b32_e32 v4, 0, v4, vcc
	v_cmp_nlt_f32_e32 vcc, s21, v0
	s_nop 1
	v_cndmask_b32_e32 v0, v11, v3, vcc
	v_cmp_nlt_f32_e32 vcc, s21, v2
	s_nop 1
	v_cndmask_b32_e32 v2, v11, v4, vcc
	v_sub_f32_e32 v0, v0, v2
	v_add_f32_e32 v0, v5, v0
	s_nop 0
	v_readfirstlane_b32 s14, v0
	s_cbranch_scc1 .LBB0_672
	s_load_dwordx2 s[12:13], s[0:1], 0x68
	v_readlane_b32 s18, v254, 60
	v_readlane_b32 s19, v254, 61
	s_lshl_b32 s18, s18, 7
	s_ashr_i32 s19, s18, 31
	s_lshl_b64 s[18:19], s[18:19], 2
	s_waitcnt lgkmcnt(0)
	s_add_u32 s44, s12, s18
	s_addc_u32 s45, s13, s19
	s_cmpk_eq_i32 s29, 0x100
	v_readlane_b32 s13, v254, 59
	s_cselect_b64 s[46:47], -1, 0
	s_lshl_b32 s12, s13, 2
	s_and_b32 s12, s12, 0xffffff80
	s_and_b32 s13, s13, 31
	s_or_b32 s60, s12, s13
	s_add_u32 s48, s10, 0xed00000
	s_addc_u32 s49, s11, 0
	s_add_u32 s50, s10, 0x8d00000
	s_addc_u32 s51, s11, 0
	s_add_u32 s52, s10, 0xad00000
	v_sub_f32_e64 v192, 1.0, s15
	s_addc_u32 s53, s11, 0
	s_mov_b32 s15, s14
	s_mov_b32 s61, 0
	s_cmp_lg_u32 s101, 0
	s_cbranch_scc1 .Lph1_att
	s_bitcmp1_b32 s2, 3
	s_cbranch_scc0 .Lph1_att
	s_mov_b32 s101, 1
	v_readlane_b32 s12, v254, 60
	s_nop 0
	s_lshl_b32 s12, s12, 10
	s_ashr_i32 s13, s12, 31
	s_lshl_b64 s[12:13], s[12:13], 2
	v_writelane_b32 v255, s12, 0
	s_nop 0
	v_writelane_b32 v255, s13, 1
	s_branch .LBB0_847
